# row-wise phases: hand-written loop, parameter vectors hoisted to registers (batch vectors reloaded on change), A/B register sets with one-row prefetch issued before stores, counted vmcnt, DPP wave red
# speedup vs baseline: 1.0871x; 1.0624x over previous
.LBB0_269:
	v_readlane_b32 s76, v251, 39
	s_cmp_lt_u32 s22, 5
	v_readlane_b32 s77, v251, 40
	v_mov_b32_e32 v1, v220
	s_mov_b32 s5, s2
	s_cselect_b32 s39, s77, 0
	s_cselect_b32 s38, s76, 0
	s_lshl_b32 s42, s5, 3
	v_ashrrev_i32_e32 v0, 6, v1
	v_and_b32_e32 v2, 63, v1
	v_add_u32_e32 v60, s42, v0
	s_mov_b32 s5, 0x8000
	v_cmp_gt_i32_e32 vcc, s5, v60
	s_waitcnt vmcnt(0)
	v_mov_b32_e32 v63, 0
	v_lshlrev_b32_e32 v164, 3, v2
	v_mov_b32_e32 v62, 0
	v_mov_b32_e32 v69, 0
	v_mov_b32_e32 v68, 0
	v_mov_b32_e32 v65, 0
	v_mov_b32_e32 v64, 0
	v_mov_b32_e32 v67, 0
	v_mov_b32_e32 v66, 0
	v_mov_b32_e32 v77, 0
	v_mov_b32_e32 v76, 0
	v_mov_b32_e32 v75, 0
	v_mov_b32_e32 v74, 0
	v_mov_b32_e32 v73, 0
	v_mov_b32_e32 v72, 0
	v_mov_b32_e32 v71, 0
	v_mov_b32_e32 v70, 0
	v_readlane_b32 s78, v251, 41
	v_readlane_b32 s79, v251, 42
	v_readlane_b32 s80, v251, 43
	v_readlane_b32 s81, v251, 44
	v_readlane_b32 s82, v251, 45
	v_readlane_b32 s83, v251, 46
	v_readlane_b32 s84, v251, 47
	v_readlane_b32 s85, v251, 48
	v_readlane_b32 s86, v251, 49
	v_readlane_b32 s87, v251, 50
	v_readlane_b32 s88, v251, 51
	v_readlane_b32 s89, v251, 52
	v_readlane_b32 s90, v251, 53
	v_readlane_b32 s91, v251, 54
	s_movk_i32 s95, 0x7fff
	s_movk_i32 s11, 0x7ff
	s_mov_b64 s[40:41], exec
	v_and_b32_e32 v160, 63, v220
	v_lshrrev_b32_e32 v162, 6, v220
	v_lshlrev_b32_e32 v161, 3, v160
	v_lshlrev_b32_e32 v160, 4, v160
	v_readfirstlane_b32 s5, v162
	s_lshl_b32 s46, s2, 3
	s_nop 3
	s_add_i32 s68, s46, s5
	s_lshl_b32 s69, s94, 3
	v_readfirstlane_b32 s5, v86
	s_nop 3
	v_readlane_b32 s14, v251, 25
	v_readlane_b32 s15, v251, 26
	v_readlane_b32 s76, v254, 51
	v_readlane_b32 s77, v254, 52
	s_mov_b64 s[42:43], s[0:1]
	s_cmp_lg_u64 s[42:43], 0
	s_cbranch_scc0 .Lrw_i1
	global_load_dwordx4 v[80:83], v160, s[54:55] offset:0
	global_load_dwordx4 v[84:87], v160, s[54:55] offset:1024
	global_load_dwordx4 v[88:91], v160, s[54:55] offset:2048
	global_load_dwordx4 v[92:95], v160, s[54:55] offset:3072
.Lrw_i1:
	s_cmp_lg_u64 s[56:57], 0
	s_cbranch_scc0 .Lrw_i2
	global_load_dwordx4 v[112:115], v160, s[28:29] offset:0
	global_load_dwordx4 v[116:119], v160, s[28:29] offset:1024
	global_load_dwordx4 v[120:123], v160, s[28:29] offset:2048
	global_load_dwordx4 v[124:127], v160, s[28:29] offset:3072
	s_cmp_lg_u64 s[62:63], 0
	s_cbranch_scc0 .Lrw_i2
	global_load_dwordx4 v[188:191], v160, s[64:65] offset:0
	global_load_dwordx4 v[192:195], v160, s[64:65] offset:1024
	global_load_dwordx4 v[196:199], v160, s[64:65] offset:2048
	global_load_dwordx4 v[200:203], v160, s[64:65] offset:3072
.Lrw_i2:
	s_cmp_lg_u64 s[38:39], 0
	s_cbranch_scc0 .Lrw_lxb_i
	s_lshl_b32 s0, s68, 12
	s_add_u32 s46, s38, s0
	s_addc_u32 s47, s39, 0
	global_load_dwordx4 v[0:3], v160, s[46:47] offset:0
	global_load_dwordx4 v[4:7], v160, s[46:47] offset:1024
	global_load_dwordx4 v[8:11], v160, s[46:47] offset:2048
	global_load_dwordx4 v[12:15], v160, s[46:47] offset:3072
	s_branch .Lrw_ly_i
.Lrw_lxb_i:
	s_lshl_b32 s0, s68, 11
	s_add_u32 s46, s14, s0
	s_addc_u32 s47, s15, 0
	global_load_dwordx2 v[0:1], v161, s[46:47] offset:0
	global_load_dwordx2 v[2:3], v161, s[46:47] offset:512
	global_load_dwordx2 v[4:5], v161, s[46:47] offset:1024
	global_load_dwordx2 v[6:7], v161, s[46:47] offset:1536
.Lrw_ly_i:
	s_cmp_lg_u64 s[42:43], 0
	s_cbranch_scc0 .Lrw_lend_i
	s_lshl_b32 s0, s68, 11
	s_add_u32 s46, s42, s0
	s_addc_u32 s47, s43, 0
	global_load_dwordx2 v[16:17], v161, s[46:47] offset:0
	global_load_dwordx2 v[18:19], v161, s[46:47] offset:512
	global_load_dwordx2 v[20:21], v161, s[46:47] offset:1024
	global_load_dwordx2 v[22:23], v161, s[46:47] offset:1536
.Lrw_lend_i:
	s_lshr_b32 s78, s68, 12
	s_mul_i32 s1, s78, 0x9000
	s_lshl_b32 s79, s78, 13
	s_cmp_lg_u64 s[42:43], 0
	s_cbranch_scc0 .Lrw_v1_i
	s_add_u32 s50, s52, s1
	s_addc_u32 s51, s53, 0
	global_load_dwordx4 v[96:99], v160, s[50:51] offset:0
	global_load_dwordx4 v[100:103], v160, s[50:51] offset:1024
	global_load_dwordx4 v[104:107], v160, s[50:51] offset:2048
	global_load_dwordx4 v[108:111], v160, s[50:51] offset:3072
.Lrw_v1_i:
	s_cmp_lg_u64 s[56:57], 0
	s_cbranch_scc0 .Lrw_vend_i
	s_add_u32 s50, s60, s1
	s_addc_u32 s51, s61, 0
	global_load_dwordx4 v[128:131], v160, s[50:51] offset:0
	global_load_dwordx4 v[132:135], v160, s[50:51] offset:1024
	global_load_dwordx4 v[136:139], v160, s[50:51] offset:2048
	global_load_dwordx4 v[140:143], v160, s[50:51] offset:3072
	s_add_u32 s50, s58, s1
	s_addc_u32 s51, s59, 0
	global_load_dwordx4 v[144:147], v160, s[50:51] offset:0
	global_load_dwordx4 v[148:151], v160, s[50:51] offset:1024
	global_load_dwordx4 v[152:155], v160, s[50:51] offset:2048
	global_load_dwordx4 v[156:159], v160, s[50:51] offset:3072
	s_cmp_lg_u64 s[62:63], 0
	s_cbranch_scc0 .Lrw_vend_i
	s_add_u32 s50, s24, s79
	s_addc_u32 s51, s25, 0
	global_load_dwordx4 v[204:207], v160, s[50:51] offset:0
	global_load_dwordx4 v[208:211], v160, s[50:51] offset:1024
	global_load_dwordx4 v[212:215], v160, s[50:51] offset:2048
	global_load_dwordx4 v[216:219], v160, s[50:51] offset:3072
	s_add_u32 s50, s66, s79
	s_addc_u32 s51, s67, 0
	global_load_dwordx4 v[8:11], v160, s[50:51] offset:0
	global_load_dwordx4 v[12:15], v160, s[50:51] offset:1024
	global_load_dwordx4 v[32:35], v160, s[50:51] offset:2048
	global_load_dwordx4 v[36:39], v160, s[50:51] offset:3072
.Lrw_vend_i:
	s_mov_b32 s81, 1
.Lrw_loop:
	s_add_i32 s80, s68, s69
	s_cmp_lt_u32 s80, 0x8000
	s_cbranch_scc0 .Lrw_nopf_A
	s_cmp_lg_u64 s[38:39], 0
	s_cbranch_scc0 .Lrw_lxb_pA
	s_lshl_b32 s0, s80, 12
	s_add_u32 s46, s38, s0
	s_addc_u32 s47, s39, 0
	global_load_dwordx4 v[24:27], v160, s[46:47] offset:0
	global_load_dwordx4 v[28:31], v160, s[46:47] offset:1024
	global_load_dwordx4 v[32:35], v160, s[46:47] offset:2048
	global_load_dwordx4 v[36:39], v160, s[46:47] offset:3072
	s_branch .Lrw_ly_pA
.Lrw_lxb_pA:
	s_lshl_b32 s0, s80, 11
	s_add_u32 s46, s14, s0
	s_addc_u32 s47, s15, 0
	global_load_dwordx2 v[24:25], v161, s[46:47] offset:0
	global_load_dwordx2 v[26:27], v161, s[46:47] offset:512
	global_load_dwordx2 v[28:29], v161, s[46:47] offset:1024
	global_load_dwordx2 v[30:31], v161, s[46:47] offset:1536
.Lrw_ly_pA:
	s_cmp_lg_u64 s[42:43], 0
	s_cbranch_scc0 .Lrw_lend_pA
	s_lshl_b32 s0, s80, 11
	s_add_u32 s46, s42, s0
	s_addc_u32 s47, s43, 0
	global_load_dwordx2 v[40:41], v161, s[46:47] offset:0
	global_load_dwordx2 v[42:43], v161, s[46:47] offset:512
	global_load_dwordx2 v[44:45], v161, s[46:47] offset:1024
	global_load_dwordx2 v[46:47], v161, s[46:47] offset:1536
.Lrw_lend_pA:
	s_cmp_eq_u32 s81, 0
	s_cbranch_scc1 .Lrw_rel_A
	s_mov_b32 s81, 0
	s_cmp_lg_u64 s[42:43], 0
	s_cbranch_scc0 .Lrw_s4_A
	s_waitcnt vmcnt(8)
	s_branch .Lrw_go_A
.Lrw_s4_A:
	s_waitcnt vmcnt(4)
	s_branch .Lrw_go_A
.Lrw_rel_A:
	s_cmp_lg_u64 s[42:43], 0
	s_cbranch_scc0 .Lrw_r0_A
	s_cmp_lg_u64 s[56:57], 0
	s_cbranch_scc0 .Lrw_r6_A
	s_cmp_lg_u64 s[62:63], 0
	s_cbranch_scc0 .Lrw_r1_A
	s_waitcnt vmcnt(20)
	s_branch .Lrw_go_A
.Lrw_r1_A:
	s_waitcnt vmcnt(16)
	s_branch .Lrw_go_A
.Lrw_r6_A:
	s_waitcnt vmcnt(12)
	s_branch .Lrw_go_A
.Lrw_r0_A:
	s_waitcnt vmcnt(8)
	s_branch .Lrw_go_A

.Lrw_go_A:
	s_cmp_lg_u64 s[38:39], 0
	s_cbranch_scc0 .Lrw_uxb_A
	v_mov_b64_e32 v[48:49], v[0:1]
	v_mov_b64_e32 v[50:51], v[2:3]
	v_mov_b64_e32 v[52:53], v[4:5]
	v_mov_b64_e32 v[54:55], v[6:7]
	v_mov_b64_e32 v[56:57], v[8:9]
	v_mov_b64_e32 v[58:59], v[10:11]
	v_mov_b64_e32 v[60:61], v[12:13]
	v_mov_b64_e32 v[62:63], v[14:15]
	s_branch .Lrw_ux_A
.Lrw_uxb_A:
	v_lshlrev_b32_e32 v48, 16, v0
	v_and_b32_e32 v49, 0xffff0000, v0
	v_lshlrev_b32_e32 v50, 16, v1
	v_and_b32_e32 v51, 0xffff0000, v1
	v_lshlrev_b32_e32 v52, 16, v2
	v_and_b32_e32 v53, 0xffff0000, v2
	v_lshlrev_b32_e32 v54, 16, v3
	v_and_b32_e32 v55, 0xffff0000, v3
	v_lshlrev_b32_e32 v56, 16, v4
	v_and_b32_e32 v57, 0xffff0000, v4
	v_lshlrev_b32_e32 v58, 16, v5
	v_and_b32_e32 v59, 0xffff0000, v5
	v_lshlrev_b32_e32 v60, 16, v6
	v_and_b32_e32 v61, 0xffff0000, v6
	v_lshlrev_b32_e32 v62, 16, v7
	v_and_b32_e32 v63, 0xffff0000, v7
.Lrw_ux_A:
	s_cmp_lg_u64 s[42:43], 0
	s_cbranch_scc0 .Lrw_noy_A
	v_lshlrev_b32_e32 v64, 16, v16
	v_and_b32_e32 v65, 0xffff0000, v16
	v_lshlrev_b32_e32 v66, 16, v17
	v_and_b32_e32 v67, 0xffff0000, v17
	v_lshlrev_b32_e32 v68, 16, v18
	v_and_b32_e32 v69, 0xffff0000, v18
	v_lshlrev_b32_e32 v70, 16, v19
	v_and_b32_e32 v71, 0xffff0000, v19
	v_lshlrev_b32_e32 v72, 16, v20
	v_and_b32_e32 v73, 0xffff0000, v20
	v_lshlrev_b32_e32 v74, 16, v21
	v_and_b32_e32 v75, 0xffff0000, v21
	v_lshlrev_b32_e32 v76, 16, v22
	v_and_b32_e32 v77, 0xffff0000, v22
	v_lshlrev_b32_e32 v78, 16, v23
	v_and_b32_e32 v79, 0xffff0000, v23
	v_mul_f32_e32 v162, v64, v64
	v_mul_f32_e32 v163, v65, v65
	v_fmac_f32_e32 v162, v66, v66
	v_fmac_f32_e32 v163, v67, v67
	v_fmac_f32_e32 v162, v68, v68
	v_fmac_f32_e32 v163, v69, v69
	v_fmac_f32_e32 v162, v70, v70
	v_fmac_f32_e32 v163, v71, v71
	v_fmac_f32_e32 v162, v72, v72
	v_fmac_f32_e32 v163, v73, v73
	v_fmac_f32_e32 v162, v74, v74
	v_fmac_f32_e32 v163, v75, v75
	v_fmac_f32_e32 v162, v76, v76
	v_fmac_f32_e32 v163, v77, v77
	v_fmac_f32_e32 v162, v78, v78
	v_fmac_f32_e32 v163, v79, v79
	v_add_f32_e32 v162, v162, v163
	s_nop 1
	v_add_f32_dpp v162, v162, v162 quad_perm:[1,0,3,2] row_mask:0xf bank_mask:0xf
	s_nop 1
	v_add_f32_dpp v162, v162, v162 quad_perm:[2,3,0,1] row_mask:0xf bank_mask:0xf
	s_nop 1
	v_add_f32_dpp v162, v162, v162 row_half_mirror row_mask:0xf bank_mask:0xf
	s_nop 1
	v_add_f32_dpp v162, v162, v162 row_mirror row_mask:0xf bank_mask:0xf
	s_nop 1
	v_readlane_b32 s48, v162, 0
	v_readlane_b32 s49, v162, 16
	v_readlane_b32 s50, v162, 32
	v_readlane_b32 s51, v162, 48
	s_nop 1
	v_mov_b32_e32 v163, s48
	v_add_f32_e32 v163, s49, v163
	v_add_f32_e32 v163, s50, v163
	v_add_f32_e32 v163, s51, v163
	v_fmamk_f32 v163, v163, 0x3a800000, v221
	v_rsq_f32_e32 v163, v163
	s_nop 0
	v_mul_f32_e32 v163, s5, v163
	v_mul_f32_e32 v64, v64, v163
	v_mul_f32_e32 v64, v96, v64
	v_fmac_f32_e32 v48, v80, v64
	v_mul_f32_e32 v65, v65, v163
	v_mul_f32_e32 v65, v97, v65
	v_fmac_f32_e32 v49, v81, v65
	v_mul_f32_e32 v66, v66, v163
	v_mul_f32_e32 v66, v98, v66
	v_fmac_f32_e32 v50, v82, v66
	v_mul_f32_e32 v67, v67, v163
	v_mul_f32_e32 v67, v99, v67
	v_fmac_f32_e32 v51, v83, v67
	v_mul_f32_e32 v68, v68, v163
	v_mul_f32_e32 v68, v100, v68
	v_fmac_f32_e32 v52, v84, v68
	v_mul_f32_e32 v69, v69, v163
	v_mul_f32_e32 v69, v101, v69
	v_fmac_f32_e32 v53, v85, v69
	v_mul_f32_e32 v70, v70, v163
	v_mul_f32_e32 v70, v102, v70
	v_fmac_f32_e32 v54, v86, v70
	v_mul_f32_e32 v71, v71, v163
	v_mul_f32_e32 v71, v103, v71
	v_fmac_f32_e32 v55, v87, v71
	v_mul_f32_e32 v72, v72, v163
	v_mul_f32_e32 v72, v104, v72
	v_fmac_f32_e32 v56, v88, v72
	v_mul_f32_e32 v73, v73, v163
	v_mul_f32_e32 v73, v105, v73
	v_fmac_f32_e32 v57, v89, v73
	v_mul_f32_e32 v74, v74, v163
	v_mul_f32_e32 v74, v106, v74
	v_fmac_f32_e32 v58, v90, v74
	v_mul_f32_e32 v75, v75, v163
	v_mul_f32_e32 v75, v107, v75
	v_fmac_f32_e32 v59, v91, v75
	v_mul_f32_e32 v76, v76, v163
	v_mul_f32_e32 v76, v108, v76
	v_fmac_f32_e32 v60, v92, v76
	v_mul_f32_e32 v77, v77, v163
	v_mul_f32_e32 v77, v109, v77
	v_fmac_f32_e32 v61, v93, v77
	v_mul_f32_e32 v78, v78, v163
	v_mul_f32_e32 v78, v110, v78
	v_fmac_f32_e32 v62, v94, v78
	v_mul_f32_e32 v79, v79, v163
	v_mul_f32_e32 v79, v111, v79
	v_fmac_f32_e32 v63, v95, v79
	v_cvt_pk_bf16_f32 v180, v48, v49
	v_cvt_pk_bf16_f32 v181, v50, v51
	v_cvt_pk_bf16_f32 v182, v52, v53
	v_cvt_pk_bf16_f32 v183, v54, v55
	v_cvt_pk_bf16_f32 v184, v56, v57
	v_cvt_pk_bf16_f32 v185, v58, v59
	v_cvt_pk_bf16_f32 v186, v60, v61
	v_cvt_pk_bf16_f32 v187, v62, v63
.Lrw_noy_A:
	s_cmp_lg_u64 s[56:57], 0
	s_cbranch_scc0 .Lrw_noh_A
	v_mul_f32_e32 v162, v48, v48
	v_mul_f32_e32 v163, v49, v49
	v_fmac_f32_e32 v162, v50, v50
	v_fmac_f32_e32 v163, v51, v51
	v_fmac_f32_e32 v162, v52, v52
	v_fmac_f32_e32 v163, v53, v53
	v_fmac_f32_e32 v162, v54, v54
	v_fmac_f32_e32 v163, v55, v55
	v_fmac_f32_e32 v162, v56, v56
	v_fmac_f32_e32 v163, v57, v57
	v_fmac_f32_e32 v162, v58, v58
	v_fmac_f32_e32 v163, v59, v59
	v_fmac_f32_e32 v162, v60, v60
	v_fmac_f32_e32 v163, v61, v61
	v_fmac_f32_e32 v162, v62, v62
	v_fmac_f32_e32 v163, v63, v63
	v_add_f32_e32 v162, v162, v163
	s_nop 1
	v_add_f32_dpp v162, v162, v162 quad_perm:[1,0,3,2] row_mask:0xf bank_mask:0xf
	s_nop 1
	v_add_f32_dpp v162, v162, v162 quad_perm:[2,3,0,1] row_mask:0xf bank_mask:0xf
	s_nop 1
	v_add_f32_dpp v162, v162, v162 row_half_mirror row_mask:0xf bank_mask:0xf
	s_nop 1
	v_add_f32_dpp v162, v162, v162 row_mirror row_mask:0xf bank_mask:0xf
	s_nop 1
	v_readlane_b32 s48, v162, 0
	v_readlane_b32 s49, v162, 16
	v_readlane_b32 s50, v162, 32
	v_readlane_b32 s51, v162, 48
	s_nop 1
	v_mov_b32_e32 v163, s48
	v_add_f32_e32 v163, s49, v163
	v_add_f32_e32 v163, s50, v163
	v_add_f32_e32 v163, s51, v163
	v_fmamk_f32 v163, v163, 0x3a800000, v221
	v_rsq_f32_e32 v163, v163
	s_nop 0
	v_mul_f32_e32 v48, v48, v163
	v_mul_f32_e32 v49, v49, v163
	v_mul_f32_e32 v50, v50, v163
	v_mul_f32_e32 v51, v51, v163
	v_mul_f32_e32 v52, v52, v163
	v_mul_f32_e32 v53, v53, v163
	v_mul_f32_e32 v54, v54, v163
	v_mul_f32_e32 v55, v55, v163
	v_mul_f32_e32 v56, v56, v163
	v_mul_f32_e32 v57, v57, v163
	v_mul_f32_e32 v58, v58, v163
	v_mul_f32_e32 v59, v59, v163
	v_mul_f32_e32 v60, v60, v163
	v_mul_f32_e32 v61, v61, v163
	v_mul_f32_e32 v62, v62, v163
	v_mul_f32_e32 v63, v63, v163
	v_mul_f32_e32 v64, v112, v48
	v_add_f32_e32 v162, 1.0, v128
	v_fma_f32 v64, v162, v64, v144
	v_mul_f32_e32 v65, v113, v49
	v_add_f32_e32 v162, 1.0, v129
	v_fma_f32 v65, v162, v65, v145
	v_mul_f32_e32 v66, v114, v50
	v_add_f32_e32 v162, 1.0, v130
	v_fma_f32 v66, v162, v66, v146
	v_mul_f32_e32 v67, v115, v51
	v_add_f32_e32 v162, 1.0, v131
	v_fma_f32 v67, v162, v67, v147
	v_cvt_pk_bf16_f32 v236, v64, v65
	v_cvt_pk_bf16_f32 v237, v66, v67
	v_mul_f32_e32 v68, v116, v52
	v_add_f32_e32 v162, 1.0, v132
	v_fma_f32 v68, v162, v68, v148
	v_mul_f32_e32 v69, v117, v53
	v_add_f32_e32 v162, 1.0, v133
	v_fma_f32 v69, v162, v69, v149
	v_mul_f32_e32 v70, v118, v54
	v_add_f32_e32 v162, 1.0, v134
	v_fma_f32 v70, v162, v70, v150
	v_mul_f32_e32 v71, v119, v55
	v_add_f32_e32 v162, 1.0, v135
	v_fma_f32 v71, v162, v71, v151
	v_cvt_pk_bf16_f32 v238, v68, v69
	v_cvt_pk_bf16_f32 v239, v70, v71
	v_mul_f32_e32 v72, v120, v56
	v_add_f32_e32 v162, 1.0, v136
	v_fma_f32 v72, v162, v72, v152
	v_mul_f32_e32 v73, v121, v57
	v_add_f32_e32 v162, 1.0, v137
	v_fma_f32 v73, v162, v73, v153
	v_mul_f32_e32 v74, v122, v58
	v_add_f32_e32 v162, 1.0, v138
	v_fma_f32 v74, v162, v74, v154
	v_mul_f32_e32 v75, v123, v59
	v_add_f32_e32 v162, 1.0, v139
	v_fma_f32 v75, v162, v75, v155
	v_cvt_pk_bf16_f32 v240, v72, v73
	v_cvt_pk_bf16_f32 v241, v74, v75
	v_mul_f32_e32 v76, v124, v60
	v_add_f32_e32 v162, 1.0, v140
	v_fma_f32 v76, v162, v76, v156
	v_mul_f32_e32 v77, v125, v61
	v_add_f32_e32 v162, 1.0, v141
	v_fma_f32 v77, v162, v77, v157
	v_mul_f32_e32 v78, v126, v62
	v_add_f32_e32 v162, 1.0, v142
	v_fma_f32 v78, v162, v78, v158
	v_mul_f32_e32 v79, v127, v63
	v_add_f32_e32 v162, 1.0, v143
	v_fma_f32 v79, v162, v79, v159
	v_cvt_pk_bf16_f32 v242, v76, v77
	v_cvt_pk_bf16_f32 v243, v78, v79
	s_cmp_lg_u64 s[62:63], 0
	s_cbranch_scc0 .Lrw_noh_A
	v_mul_f32_e32 v64, v188, v48
	v_add_f32_e32 v162, 1.0, v204
	v_fma_f32 v64, v162, v64, v8
	v_mul_f32_e32 v65, v189, v49
	v_add_f32_e32 v162, 1.0, v205
	v_fma_f32 v65, v162, v65, v9
	v_mul_f32_e32 v66, v190, v50
	v_add_f32_e32 v162, 1.0, v206
	v_fma_f32 v66, v162, v66, v10
	v_mul_f32_e32 v67, v191, v51
	v_add_f32_e32 v162, 1.0, v207
	v_fma_f32 v67, v162, v67, v11
	v_mul_f32_e32 v68, v192, v52
	v_add_f32_e32 v162, 1.0, v208
	v_fma_f32 v68, v162, v68, v12
	v_mul_f32_e32 v69, v193, v53
	v_add_f32_e32 v162, 1.0, v209
	v_fma_f32 v69, v162, v69, v13
	v_mul_f32_e32 v70, v194, v54
	v_add_f32_e32 v162, 1.0, v210
	v_fma_f32 v70, v162, v70, v14
	v_mul_f32_e32 v71, v195, v55
	v_add_f32_e32 v162, 1.0, v211
	v_fma_f32 v71, v162, v71, v15
	v_mul_f32_e32 v72, v196, v56
	v_add_f32_e32 v162, 1.0, v212
	v_fma_f32 v72, v162, v72, v32
	v_mul_f32_e32 v73, v197, v57
	v_add_f32_e32 v162, 1.0, v213
	v_fma_f32 v73, v162, v73, v33
	v_mul_f32_e32 v74, v198, v58
	v_add_f32_e32 v162, 1.0, v214
	v_fma_f32 v74, v162, v74, v34
	v_mul_f32_e32 v75, v199, v59
	v_add_f32_e32 v162, 1.0, v215
	v_fma_f32 v75, v162, v75, v35
	v_mul_f32_e32 v76, v200, v60
	v_add_f32_e32 v162, 1.0, v216
	v_fma_f32 v76, v162, v76, v36
	v_mul_f32_e32 v77, v201, v61
	v_add_f32_e32 v162, 1.0, v217
	v_fma_f32 v77, v162, v77, v37
	v_mul_f32_e32 v78, v202, v62
	v_add_f32_e32 v162, 1.0, v218
	v_fma_f32 v78, v162, v78, v38
	v_mul_f32_e32 v79, v203, v63
	v_add_f32_e32 v162, 1.0, v219
	v_fma_f32 v79, v162, v79, v39
	v_cvt_pk_bf16_f32 v64, v64, v65
	v_cvt_pk_bf16_f32 v65, v66, v67
	v_cvt_pk_bf16_f32 v66, v68, v69
	v_cvt_pk_bf16_f32 v67, v70, v71
	v_cvt_pk_bf16_f32 v68, v72, v73
	v_cvt_pk_bf16_f32 v69, v74, v75
	v_cvt_pk_bf16_f32 v70, v76, v77
	v_cvt_pk_bf16_f32 v71, v78, v79
.Lrw_noh_A:
	s_cmp_lt_u32 s80, 0x8000
	s_cbranch_scc0 .Lrw_nov_A
	s_lshr_b32 s0, s80, 12
	s_cmp_eq_u32 s0, s78
	s_cbranch_scc1 .Lrw_nov_A
	s_mov_b32 s78, s0
	s_mul_i32 s1, s78, 0x9000
	s_lshl_b32 s79, s78, 13
	s_cmp_lg_u64 s[42:43], 0
	s_cbranch_scc0 .Lrw_v1_A
	s_add_u32 s50, s52, s1
	s_addc_u32 s51, s53, 0
	global_load_dwordx4 v[96:99], v160, s[50:51] offset:0
	global_load_dwordx4 v[100:103], v160, s[50:51] offset:1024
	global_load_dwordx4 v[104:107], v160, s[50:51] offset:2048
	global_load_dwordx4 v[108:111], v160, s[50:51] offset:3072

.Lrw_vend_A:
.Lrw_nov_A:
	s_cmp_lg_u64 s[42:43], 0
	s_cbranch_scc0 .Lrw_st1_A
	s_cmp_eq_u32 s22, 26
	s_cbranch_scc0 .Lrw_sxb_A
	s_lshl_b32 s0, s68, 12
	s_add_u32 s46, s76, s0
	s_addc_u32 s47, s77, 0
	global_store_dwordx4 v160, v[48:51], s[46:47] offset:0
	global_store_dwordx4 v160, v[52:55], s[46:47] offset:1024
	global_store_dwordx4 v160, v[56:59], s[46:47] offset:2048
	global_store_dwordx4 v160, v[60:63], s[46:47] offset:3072
	s_branch .Lrw_st1_A
.Lrw_sxb_A:
	s_lshl_b32 s0, s68, 11
	s_add_u32 s46, s14, s0
	s_addc_u32 s47, s15, 0
	global_store_dwordx2 v161, v[180:181], s[46:47] offset:0
	global_store_dwordx2 v161, v[182:183], s[46:47] offset:512
	global_store_dwordx2 v161, v[184:185], s[46:47] offset:1024
	global_store_dwordx2 v161, v[186:187], s[46:47] offset:1536
.Lrw_st1_A:
	s_cmp_lg_u64 s[56:57], 0
	s_cbranch_scc0 .Lrw_st2_A
	s_lshl_b32 s0, s68, 11
	s_add_u32 s46, s56, s0
	s_addc_u32 s47, s57, 0
	global_store_dwordx2 v161, v[236:237], s[46:47] offset:0
	global_store_dwordx2 v161, v[238:239], s[46:47] offset:512
	global_store_dwordx2 v161, v[240:241], s[46:47] offset:1024
	global_store_dwordx2 v161, v[242:243], s[46:47] offset:1536
	s_cmp_lg_u64 s[62:63], 0
	s_cbranch_scc0 .Lrw_st2_A
	s_lshl_b32 s0, s68, 11
	s_add_u32 s46, s62, s0
	s_addc_u32 s47, s63, 0
	global_store_dwordx2 v161, v[64:65], s[46:47] offset:0
	global_store_dwordx2 v161, v[66:67], s[46:47] offset:512
	global_store_dwordx2 v161, v[68:69], s[46:47] offset:1024
	global_store_dwordx2 v161, v[70:71], s[46:47] offset:1536
.Lrw_st2_A:
	s_cmp_lt_u32 s80, 0x8000
	s_cbranch_scc0 .Lrw_done
	s_mov_b32 s68, s80
	s_add_i32 s80, s68, s69
	s_cmp_lt_u32 s80, 0x8000
	s_cbranch_scc0 .Lrw_nopf_B
	s_cmp_lg_u64 s[38:39], 0
	s_cbranch_scc0 .Lrw_lxb_pB
	s_lshl_b32 s0, s80, 12
	s_add_u32 s46, s38, s0
	s_addc_u32 s47, s39, 0
	global_load_dwordx4 v[0:3], v160, s[46:47] offset:0
	global_load_dwordx4 v[4:7], v160, s[46:47] offset:1024
	global_load_dwordx4 v[8:11], v160, s[46:47] offset:2048
	global_load_dwordx4 v[12:15], v160, s[46:47] offset:3072
	s_branch .Lrw_ly_pB
.Lrw_lxb_pB:
	s_lshl_b32 s0, s80, 11
	s_add_u32 s46, s14, s0
	s_addc_u32 s47, s15, 0
	global_load_dwordx2 v[0:1], v161, s[46:47] offset:0
	global_load_dwordx2 v[2:3], v161, s[46:47] offset:512
	global_load_dwordx2 v[4:5], v161, s[46:47] offset:1024
	global_load_dwordx2 v[6:7], v161, s[46:47] offset:1536
.Lrw_ly_pB:
	s_cmp_lg_u64 s[42:43], 0
	s_cbranch_scc0 .Lrw_lend_pB
	s_lshl_b32 s0, s80, 11
	s_add_u32 s46, s42, s0
	s_addc_u32 s47, s43, 0
	global_load_dwordx2 v[16:17], v161, s[46:47] offset:0
	global_load_dwordx2 v[18:19], v161, s[46:47] offset:512
	global_load_dwordx2 v[20:21], v161, s[46:47] offset:1024
	global_load_dwordx2 v[22:23], v161, s[46:47] offset:1536

.Lrw_go_B:
	s_cmp_lg_u64 s[38:39], 0
	s_cbranch_scc0 .Lrw_uxb_B
	v_mov_b64_e32 v[48:49], v[24:25]
	v_mov_b64_e32 v[50:51], v[26:27]
	v_mov_b64_e32 v[52:53], v[28:29]
	v_mov_b64_e32 v[54:55], v[30:31]
	v_mov_b64_e32 v[56:57], v[32:33]
	v_mov_b64_e32 v[58:59], v[34:35]
	v_mov_b64_e32 v[60:61], v[36:37]
	v_mov_b64_e32 v[62:63], v[38:39]
	s_branch .Lrw_ux_B
.Lrw_uxb_B:
	v_lshlrev_b32_e32 v48, 16, v24
	v_and_b32_e32 v49, 0xffff0000, v24
	v_lshlrev_b32_e32 v50, 16, v25
	v_and_b32_e32 v51, 0xffff0000, v25
	v_lshlrev_b32_e32 v52, 16, v26
	v_and_b32_e32 v53, 0xffff0000, v26
	v_lshlrev_b32_e32 v54, 16, v27
	v_and_b32_e32 v55, 0xffff0000, v27
	v_lshlrev_b32_e32 v56, 16, v28
	v_and_b32_e32 v57, 0xffff0000, v28
	v_lshlrev_b32_e32 v58, 16, v29
	v_and_b32_e32 v59, 0xffff0000, v29
	v_lshlrev_b32_e32 v60, 16, v30
	v_and_b32_e32 v61, 0xffff0000, v30
	v_lshlrev_b32_e32 v62, 16, v31
	v_and_b32_e32 v63, 0xffff0000, v31
.Lrw_ux_B:
	s_cmp_lg_u64 s[42:43], 0
	s_cbranch_scc0 .Lrw_noy_B
	v_lshlrev_b32_e32 v64, 16, v40
	v_and_b32_e32 v65, 0xffff0000, v40
	v_lshlrev_b32_e32 v66, 16, v41
	v_and_b32_e32 v67, 0xffff0000, v41
	v_lshlrev_b32_e32 v68, 16, v42
	v_and_b32_e32 v69, 0xffff0000, v42
	v_lshlrev_b32_e32 v70, 16, v43
	v_and_b32_e32 v71, 0xffff0000, v43
	v_lshlrev_b32_e32 v72, 16, v44
	v_and_b32_e32 v73, 0xffff0000, v44
	v_lshlrev_b32_e32 v74, 16, v45
	v_and_b32_e32 v75, 0xffff0000, v45
	v_lshlrev_b32_e32 v76, 16, v46
	v_and_b32_e32 v77, 0xffff0000, v46
	v_lshlrev_b32_e32 v78, 16, v47
	v_and_b32_e32 v79, 0xffff0000, v47
	v_mul_f32_e32 v162, v64, v64
	v_mul_f32_e32 v163, v65, v65
	v_fmac_f32_e32 v162, v66, v66
	v_fmac_f32_e32 v163, v67, v67
	v_fmac_f32_e32 v162, v68, v68
	v_fmac_f32_e32 v163, v69, v69
	v_fmac_f32_e32 v162, v70, v70
	v_fmac_f32_e32 v163, v71, v71
	v_fmac_f32_e32 v162, v72, v72
	v_fmac_f32_e32 v163, v73, v73
	v_fmac_f32_e32 v162, v74, v74
	v_fmac_f32_e32 v163, v75, v75
	v_fmac_f32_e32 v162, v76, v76
	v_fmac_f32_e32 v163, v77, v77
	v_fmac_f32_e32 v162, v78, v78
	v_fmac_f32_e32 v163, v79, v79
	v_add_f32_e32 v162, v162, v163
	s_nop 1
	v_add_f32_dpp v162, v162, v162 quad_perm:[1,0,3,2] row_mask:0xf bank_mask:0xf
	s_nop 1
	v_add_f32_dpp v162, v162, v162 quad_perm:[2,3,0,1] row_mask:0xf bank_mask:0xf
	s_nop 1
	v_add_f32_dpp v162, v162, v162 row_half_mirror row_mask:0xf bank_mask:0xf
	s_nop 1
	v_add_f32_dpp v162, v162, v162 row_mirror row_mask:0xf bank_mask:0xf
	s_nop 1
	v_readlane_b32 s48, v162, 0
	v_readlane_b32 s49, v162, 16
	v_readlane_b32 s50, v162, 32
	v_readlane_b32 s51, v162, 48
	s_nop 1
	v_mov_b32_e32 v163, s48
	v_add_f32_e32 v163, s49, v163
	v_add_f32_e32 v163, s50, v163
	v_add_f32_e32 v163, s51, v163
	v_fmamk_f32 v163, v163, 0x3a800000, v221
	v_rsq_f32_e32 v163, v163
	s_nop 0
	v_mul_f32_e32 v163, s5, v163
	v_mul_f32_e32 v64, v64, v163
	v_mul_f32_e32 v64, v96, v64
	v_fmac_f32_e32 v48, v80, v64
	v_mul_f32_e32 v65, v65, v163
	v_mul_f32_e32 v65, v97, v65
	v_fmac_f32_e32 v49, v81, v65
	v_mul_f32_e32 v66, v66, v163
	v_mul_f32_e32 v66, v98, v66
	v_fmac_f32_e32 v50, v82, v66
	v_mul_f32_e32 v67, v67, v163
	v_mul_f32_e32 v67, v99, v67
	v_fmac_f32_e32 v51, v83, v67
	v_mul_f32_e32 v68, v68, v163
	v_mul_f32_e32 v68, v100, v68
	v_fmac_f32_e32 v52, v84, v68
	v_mul_f32_e32 v69, v69, v163
	v_mul_f32_e32 v69, v101, v69
	v_fmac_f32_e32 v53, v85, v69
	v_mul_f32_e32 v70, v70, v163
	v_mul_f32_e32 v70, v102, v70
	v_fmac_f32_e32 v54, v86, v70
	v_mul_f32_e32 v71, v71, v163
	v_mul_f32_e32 v71, v103, v71
	v_fmac_f32_e32 v55, v87, v71
	v_mul_f32_e32 v72, v72, v163
	v_mul_f32_e32 v72, v104, v72
	v_fmac_f32_e32 v56, v88, v72
	v_mul_f32_e32 v73, v73, v163
	v_mul_f32_e32 v73, v105, v73
	v_fmac_f32_e32 v57, v89, v73
	v_mul_f32_e32 v74, v74, v163
	v_mul_f32_e32 v74, v106, v74
	v_fmac_f32_e32 v58, v90, v74
	v_mul_f32_e32 v75, v75, v163
	v_mul_f32_e32 v75, v107, v75
	v_fmac_f32_e32 v59, v91, v75
	v_mul_f32_e32 v76, v76, v163
	v_mul_f32_e32 v76, v108, v76
	v_fmac_f32_e32 v60, v92, v76
	v_mul_f32_e32 v77, v77, v163
	v_mul_f32_e32 v77, v109, v77
	v_fmac_f32_e32 v61, v93, v77
	v_mul_f32_e32 v78, v78, v163
	v_mul_f32_e32 v78, v110, v78
	v_fmac_f32_e32 v62, v94, v78
	v_mul_f32_e32 v79, v79, v163
	v_mul_f32_e32 v79, v111, v79
	v_fmac_f32_e32 v63, v95, v79
	v_cvt_pk_bf16_f32 v180, v48, v49
	v_cvt_pk_bf16_f32 v181, v50, v51
	v_cvt_pk_bf16_f32 v182, v52, v53
	v_cvt_pk_bf16_f32 v183, v54, v55
	v_cvt_pk_bf16_f32 v184, v56, v57
	v_cvt_pk_bf16_f32 v185, v58, v59
	v_cvt_pk_bf16_f32 v186, v60, v61
	v_cvt_pk_bf16_f32 v187, v62, v63

.Lrw_st2_B:
	s_cmp_lt_u32 s80, 0x8000
	s_cbranch_scc0 .Lrw_done
	s_mov_b32 s68, s80
	s_branch .Lrw_loop
.Lrw_done:
.LBB0_306:
	s_or_b64 exec, exec, s[40:41]
	v_readlane_b32 s16, v254, 31
	v_readlane_b32 s42, v251, 29
	v_readlane_b32 s46, v251, 31
	v_readlane_b32 s48, v251, 33
	v_readlane_b32 s66, v254, 35
	s_cmp_lg_u32 s22, 4
	v_readlane_b32 s17, v254, 32
	v_readlane_b32 s64, v254, 33
	v_readlane_b32 s43, v251, 30
	v_readlane_b32 s47, v251, 32
	v_readlane_b32 s49, v251, 34
	v_readlane_b32 s67, v254, 36
	s_movk_i32 s14, 0x5800
	v_readlane_b32 s65, v254, 34
	s_cbranch_scc1 .LBB0_336
	v_mov_b32_e32 v0, v220
	s_mov_b32 s5, s2
	s_cmpk_gt_i32 s5, 0x57f
	s_cbranch_scc1 .LBB0_330
	v_ashrrev_i32_e32 v5, 3, v0
	v_lshlrev_b32_e32 v0, 3, v0
	v_and_b32_e32 v4, 56, v0
	v_lshl_add_u32 v8, v4, 2, 0
	s_movk_i32 s0, 0x104
	v_lshlrev_b32_e32 v0, 8, v4
	v_lshlrev_b32_e32 v1, 2, v5
	v_mul_lo_u32 v9, v5, s0
	v_add3_u32 v10, v8, v0, v1
	s_lshl_b32 s7, s5, 6
	v_lshlrev_b32_e32 v164, 1, v4
	s_branch .LBB0_310
